# EpiSwiglu: 36 output pairs compute the sigmoid's -log2e multiply and 1+e add as packed ops in the reciprocal's register pair (72 fewer VALU per two epilogues); store-data hazard padded
# baseline (speedup 1.0000x reference)
.LBB0_169:
	s_mov_b32 s98, 0xbfb8aa3b
	v_mov_b32_e32 v142, v149
	v_mov_b32_e32 v180, v147
	s_add_i32 s22, 0, 0x21000
	v_add_u32_e32 v181, s88, v142
	v_lshlrev_b32_e32 v142, 4, v180
	v_lshlrev_b32_e32 v143, 6, v181
	s_waitcnt vmcnt(16)
	s_barrier
	v_add3_u32 v146, s22, v142, v143
	ds_read_b128 v[142:145], v146
	ds_read_b128 v[154:157], v146 offset:1024
	ds_read_b128 v[158:161], v146 offset:2048
	ds_read_b128 v[162:165], v146 offset:3072
	v_and_b32_e32 v150, 64, v225
	v_xor_b32_e32 v148, 16, v225
	v_add_u32_e32 v150, 64, v150
	v_cmp_lt_i32_e32 vcc, v148, v150
	s_waitcnt lgkmcnt(0)
	v_mov_b32_e32 v166, v143
	v_mov_b32_e32 v167, v144
	v_mov_b32_e32 v143, v145
	v_cndmask_b32_e32 v148, v225, v148, vcc
	v_pk_add_f32 v[142:143], v[166:167], v[142:143]
	v_lshlrev_b32_e32 v182, 2, v148
	v_add_f32_e32 v142, v142, v143
	ds_bpermute_b32 v143, v182, v142
	v_xor_b32_e32 v144, 32, v225
	v_cmp_lt_i32_e32 vcc, v144, v150
	v_mov_b32_e32 v178, v155
	v_mov_b32_e32 v179, v156
	v_cndmask_b32_e32 v144, v225, v144, vcc
	v_lshlrev_b32_e32 v183, 2, v144
	s_waitcnt lgkmcnt(0)
	v_add_f32_e32 v148, v142, v143
	ds_bpermute_b32 v150, v183, v148
	v_mov_b32_e32 v155, v157
	v_pk_add_f32 v[154:155], v[178:179], v[154:155]
	ds_read_b128 v[142:145], v146 offset:8192
	ds_read_b128 v[166:169], v146 offset:9216
	ds_read_b128 v[170:173], v146 offset:10240
	ds_read_b128 v[174:177], v146 offset:11264
	s_and_b64 vcc, exec, s[6:7]
	s_waitcnt lgkmcnt(0)
	v_add_f32_e32 v146, v148, v150
	v_add_f32_e32 v148, v154, v155
	v_mov_b32_e32 v154, v159
	v_mov_b32_e32 v155, v160
	v_mov_b32_e32 v159, v161
	v_pk_add_f32 v[154:155], v[154:155], v[158:159]
	ds_bpermute_b32 v150, v182, v148
	v_add_f32_e32 v152, v154, v155
	ds_bpermute_b32 v154, v182, v152
	v_fmamk_f32 v146, v146, 0x3a800000, v226
	v_rsq_f32_e32 v156, v146
	s_waitcnt lgkmcnt(0)
	v_add_f32_e32 v146, v148, v150
	v_mov_b32_e32 v155, v164
	v_add_f32_e32 v150, v152, v154
	v_mov_b32_e32 v154, v163
	v_mov_b32_e32 v163, v165
	v_pk_add_f32 v[154:155], v[154:155], v[162:163]
	ds_bpermute_b32 v148, v183, v146
	v_add_f32_e32 v155, v154, v155
	v_mov_b32_e32 v158, v143
	v_mov_b32_e32 v159, v144
	v_mov_b32_e32 v143, v145
	ds_bpermute_b32 v157, v182, v155
	v_pk_add_f32 v[142:143], v[158:159], v[142:143]
	ds_bpermute_b32 v152, v183, v150
	v_add_f32_e32 v142, v142, v143
	ds_bpermute_b32 v143, v182, v142
	s_waitcnt lgkmcnt(0)
	v_add_f32_e32 v146, v146, v148
	v_fmamk_f32 v146, v146, 0x3a800000, v226
	v_add_f32_e32 v148, v155, v157
	v_rsq_f32_e32 v154, v146
	v_add_f32_e32 v146, v150, v152
	ds_bpermute_b32 v150, v183, v148
	v_add_f32_e32 v145, v142, v143
	v_mov_b32_e32 v142, v167
	v_mov_b32_e32 v143, v168
	v_mov_b32_e32 v167, v169
	v_fmamk_f32 v144, v146, 0x3a800000, v226
	ds_bpermute_b32 v146, v183, v145
	v_pk_add_f32 v[142:143], v[142:143], v[166:167]
	v_rsq_f32_e32 v152, v144
	v_add_f32_e32 v142, v142, v143
	ds_bpermute_b32 v143, v182, v142
	s_waitcnt lgkmcnt(0)
	v_add_f32_e32 v144, v148, v150
	v_fmamk_f32 v144, v144, 0x3a800000, v226
	v_rsq_f32_e32 v150, v144
	v_add_f32_e32 v144, v145, v146
	v_fmamk_f32 v144, v144, 0x3a800000, v226
	v_rsq_f32_e32 v148, v144
	v_add_f32_e32 v144, v142, v143
	v_mov_b32_e32 v142, v171
	v_mov_b32_e32 v143, v172
	v_mov_b32_e32 v171, v173
	v_pk_add_f32 v[142:143], v[142:143], v[170:171]
	v_pk_mul_f32 v[158:159], v[126:127], v[156:157] op_sel_hi:[1,0]
	v_add_f32_e32 v146, v142, v143
	v_mov_b32_e32 v142, v175
	v_mov_b32_e32 v143, v176
	v_mov_b32_e32 v175, v177
	v_pk_add_f32 v[142:143], v[142:143], v[174:175]
	v_add_f32_e32 v142, v142, v143
	ds_bpermute_b32 v143, v182, v142
	v_pk_mul_f32 v[128:129], v[128:129], v[156:157] op_sel_hi:[1,0]
	v_pk_mul_f32 v[122:123], v[122:123], v[156:157] op_sel_hi:[1,0]
	v_pk_mul_f32 v[118:119], v[118:119], v[156:157] op_sel_hi:[1,0]
	s_waitcnt lgkmcnt(0)
	v_add_f32_e32 v142, v142, v143
	ds_bpermute_b32 v143, v183, v142
	v_pk_mul_f32 v[122:123], v[158:159], v[122:123]
	v_pk_mul_f32 v[124:125], v[124:125], v[156:157] op_sel_hi:[1,0]
	s_waitcnt lgkmcnt(0)
	v_add_f32_e32 v142, v142, v143
	v_pk_mul_f32 v[162:163], v[158:159], s[98:99] op_sel_hi:[1,0]
	s_nop 0
	v_exp_f32_e32 v162, v162
	v_exp_f32_e32 v163, v163
	v_pk_mul_f32 v[114:115], v[114:115], v[156:157] op_sel_hi:[1,0]
	v_pk_mul_f32 v[124:125], v[128:129], v[124:125]
	v_pk_mul_f32 v[114:115], v[118:119], v[114:115]
	v_pk_add_f32 v[162:163], v[162:163], 1.0 op_sel_hi:[1,0]
	s_nop 0
	v_rcp_f32_e32 v162, v162
	v_rcp_f32_e32 v163, v163
	v_mul_f32_e32 v127, 0xbfb8aa3b, v128
	v_exp_f32_e32 v127, v127
	v_mul_f32_e32 v143, 0xbfb8aa3b, v129
	v_exp_f32_e32 v143, v143
	v_add_f32_e32 v127, 1.0, v127
	v_rcp_f32_e32 v158, v127
	v_add_f32_e32 v127, 1.0, v143
	v_rcp_f32_e32 v159, v127
	v_pk_mul_f32 v[128:129], v[118:119], s[98:99] op_sel_hi:[1,0]
	s_nop 0
	v_exp_f32_e32 v128, v128
	v_pk_mul_f32 v[118:119], v[120:121], v[156:157] op_sel_hi:[1,0]
	v_exp_f32_e32 v129, v129
	v_pk_mul_f32 v[120:121], v[118:119], s[98:99] op_sel_hi:[1,0]
	s_nop 0
	v_exp_f32_e32 v120, v120
	v_exp_f32_e32 v121, v121
	ds_bpermute_b32 v145, v183, v144
	ds_bpermute_b32 v155, v182, v146
	v_pk_add_f32 v[128:129], v[128:129], 1.0 op_sel_hi:[1,0]
	s_nop 0
	v_rcp_f32_e32 v128, v128
	v_rcp_f32_e32 v129, v129
	v_pk_add_f32 v[120:121], v[120:121], 1.0 op_sel_hi:[1,0]
	s_nop 0
	v_rcp_f32_e32 v120, v120
	v_rcp_f32_e32 v121, v121
	s_waitcnt lgkmcnt(0)
	v_add_f32_e32 v144, v144, v145
	v_add_f32_e32 v145, v146, v155
	v_pk_mul_f32 v[116:117], v[116:117], v[156:157] op_sel_hi:[1,0]
	ds_bpermute_b32 v155, v183, v145
	v_pk_mul_f32 v[114:115], v[114:115], v[128:129]
	v_pk_mul_f32 v[116:117], v[118:119], v[116:117]
	v_lshl_add_u32 v126, s72, 8, v181
	v_pk_mul_f32 v[120:121], v[116:117], v[120:121]
	v_cvt_pk_bf16_f32 v118, v114, v115
	v_mov_b64_e32 v[114:115], s[54:55]
	v_cvt_pk_bf16_f32 v119, v120, v121
	v_mad_i64_i32 v[120:121], s[72:73], v126, s65, v[114:115]
	s_lshl_b32 s72, s35, 7
	v_pk_mul_f32 v[122:123], v[122:123], v[162:163]
	s_ashr_i32 s73, s72, 31
	v_lshlrev_b32_e32 v160, 3, v180
	v_cvt_pk_bf16_f32 v116, v122, v123
	s_lshl_b64 s[72:73], s[72:73], 1
	s_waitcnt lgkmcnt(0)
	v_pk_mul_f32 v[122:123], v[110:111], v[154:155] op_sel_hi:[1,0]
	v_ashrrev_i32_e32 v161, 31, v160
	v_pk_mul_f32 v[124:125], v[124:125], v[158:159]
	v_lshl_add_u64 v[120:121], v[120:121], 0, s[72:73]
	v_cvt_pk_bf16_f32 v117, v124, v125
	v_lshl_add_u64 v[120:121], v[120:121], 0, s[48:49]
	v_lshlrev_b64 v[110:111], 1, v[160:161]
	v_lshl_add_u64 v[120:121], v[120:121], 0, v[110:111]
	global_store_dwordx4 v[120:121], v[116:119], off
	v_pk_mul_f32 v[112:113], v[112:113], v[154:155] op_sel_hi:[1,0]
	v_pk_mul_f32 v[106:107], v[106:107], v[154:155] op_sel_hi:[1,0]
	v_pk_mul_f32 v[116:117], v[122:123], s[98:99] op_sel_hi:[1,0]
	s_nop 0
	v_exp_f32_e32 v116, v116
	v_exp_f32_e32 v117, v117
	v_mul_f32_e32 v118, 0xbfb8aa3b, v112
	v_pk_add_f32 v[116:117], v[116:117], 1.0 op_sel_hi:[1,0]
	s_nop 0
	v_rcp_f32_e32 v116, v116
	v_rcp_f32_e32 v117, v117
	v_exp_f32_e32 v118, v118
	v_pk_mul_f32 v[106:107], v[122:123], v[106:107]
	v_pk_mul_f32 v[102:103], v[102:103], v[154:155] op_sel_hi:[1,0]
	v_pk_mul_f32 v[108:109], v[108:109], v[154:155] op_sel_hi:[1,0]
	v_mul_f32_e32 v119, 0xbfb8aa3b, v113
	v_pk_mul_f32 v[106:107], v[106:107], v[116:117]
	v_add_f32_e32 v116, 1.0, v118
	v_pk_mul_f32 v[108:109], v[112:113], v[108:109]
	v_pk_mul_f32 v[112:113], v[102:103], s[98:99] op_sel_hi:[1,0]
	v_pk_mul_f32 v[98:99], v[98:99], v[154:155] op_sel_hi:[1,0]
	v_exp_f32_e32 v112, v112
	v_exp_f32_e32 v113, v113
	v_pk_mul_f32 v[98:99], v[102:103], v[98:99]
	v_pk_mul_f32 v[102:103], v[104:105], v[154:155] op_sel_hi:[1,0]
	v_pk_mul_f32 v[104:105], v[102:103], s[98:99] op_sel_hi:[1,0]
	s_nop 0
	v_exp_f32_e32 v104, v104
	v_exp_f32_e32 v105, v105
	v_pk_add_f32 v[112:113], v[112:113], 1.0 op_sel_hi:[1,0]
	v_exp_f32_e32 v119, v119
	v_rcp_f32_e32 v112, v112
	v_rcp_f32_e32 v113, v113
	v_pk_add_f32 v[104:105], v[104:105], 1.0 op_sel_hi:[1,0]
	s_nop 0
	v_rcp_f32_e32 v104, v104
	v_rcp_f32_e32 v105, v105
	v_add_f32_e32 v117, 1.0, v119
	v_pk_mul_f32 v[112:113], v[98:99], v[112:113]
	v_pk_mul_f32 v[98:99], v[100:101], v[154:155] op_sel_hi:[1,0]
	v_rcp_f32_e32 v116, v116
	v_rcp_f32_e32 v117, v117
	v_pk_mul_f32 v[98:99], v[102:103], v[98:99]
	v_cvt_pk_bf16_f32 v100, v112, v113
	v_pk_mul_f32 v[102:103], v[98:99], v[104:105]
	v_add_u32_e32 v104, 16, v126
	v_cvt_pk_bf16_f32 v101, v102, v103
	v_mad_i64_i32 v[102:103], s[74:75], v104, s65, v[114:115]
	v_lshl_add_u64 v[102:103], v[102:103], 0, s[72:73]
	v_pk_mul_f32 v[108:109], v[108:109], v[116:117]
	v_lshl_add_u64 v[102:103], v[102:103], 0, s[48:49]
	v_cvt_pk_bf16_f32 v98, v106, v107
	v_cvt_pk_bf16_f32 v99, v108, v109
	v_pk_mul_f32 v[92:93], v[92:93], v[152:153] op_sel_hi:[1,0]
	v_lshl_add_u64 v[102:103], v[102:103], 0, v[110:111]
	global_store_dwordx4 v[102:103], v[98:101], off
	v_pk_mul_f32 v[88:89], v[88:89], v[152:153] op_sel_hi:[1,0]
	s_nop 0
	v_pk_mul_f32 v[98:99], v[92:93], s[98:99] op_sel_hi:[1,0]
	s_nop 0
	v_exp_f32_e32 v98, v98
	v_exp_f32_e32 v99, v99
	v_pk_mul_f32 v[88:89], v[92:93], v[88:89]
	v_pk_add_f32 v[98:99], v[98:99], 1.0 op_sel_hi:[1,0]
	s_nop 0
	v_rcp_f32_e32 v98, v98
	v_rcp_f32_e32 v99, v99
	v_pk_mul_f32 v[92:93], v[94:95], v[152:153] op_sel_hi:[1,0]
	v_pk_mul_f32 v[84:85], v[84:85], v[152:153] op_sel_hi:[1,0]
	v_pk_mul_f32 v[90:91], v[90:91], v[152:153] op_sel_hi:[1,0]
	v_mul_f32_e32 v95, 0xbfb8aa3b, v93
	v_pk_mul_f32 v[88:89], v[88:89], v[98:99]
	v_mul_f32_e32 v98, 0xbfb8aa3b, v84
	v_pk_mul_f32 v[90:91], v[92:93], v[90:91]
	v_mul_f32_e32 v93, 0xbfb8aa3b, v85
	v_pk_mul_f32 v[80:81], v[80:81], v[152:153] op_sel_hi:[1,0]
	v_exp_f32_e32 v98, v98
	v_exp_f32_e32 v93, v93
	v_pk_mul_f32 v[80:81], v[84:85], v[80:81]
	v_pk_mul_f32 v[84:85], v[86:87], v[152:153] op_sel_hi:[1,0]
	v_mul_f32_e32 v94, 0xbfb8aa3b, v92
	v_pk_mul_f32 v[86:87], v[84:85], s[98:99] op_sel_hi:[1,0]
	s_nop 0
	v_exp_f32_e32 v86, v86
	v_exp_f32_e32 v87, v87
	v_add_f32_e32 v92, 1.0, v98
	v_add_f32_e32 v93, 1.0, v93
	v_exp_f32_e32 v94, v94
	v_exp_f32_e32 v95, v95
	v_rcp_f32_e32 v92, v92
	v_rcp_f32_e32 v93, v93
	v_pk_add_f32 v[86:87], v[86:87], 1.0 op_sel_hi:[1,0]
	s_nop 0
	v_rcp_f32_e32 v86, v86
	v_rcp_f32_e32 v87, v87
	v_add_f32_e32 v94, 1.0, v94
	v_add_f32_e32 v95, 1.0, v95
	v_pk_mul_f32 v[92:93], v[80:81], v[92:93]
	v_pk_mul_f32 v[80:81], v[82:83], v[152:153] op_sel_hi:[1,0]
	v_rcp_f32_e32 v94, v94
	v_rcp_f32_e32 v95, v95
	v_pk_mul_f32 v[80:81], v[84:85], v[80:81]
	v_cvt_pk_bf16_f32 v82, v92, v93
	v_pk_mul_f32 v[84:85], v[80:81], v[86:87]
	v_add_u32_e32 v86, 32, v126
	v_cvt_pk_bf16_f32 v83, v84, v85
	v_mad_i64_i32 v[84:85], s[74:75], v86, s65, v[114:115]
	v_lshl_add_u64 v[84:85], v[84:85], 0, s[72:73]
	v_pk_mul_f32 v[90:91], v[90:91], v[94:95]
	v_lshl_add_u64 v[84:85], v[84:85], 0, s[48:49]
	v_cvt_pk_bf16_f32 v80, v88, v89
	v_cvt_pk_bf16_f32 v81, v90, v91
	v_pk_mul_f32 v[76:77], v[76:77], v[150:151] op_sel_hi:[1,0]
	v_lshl_add_u64 v[84:85], v[84:85], 0, v[110:111]
	global_store_dwordx4 v[84:85], v[80:83], off
	v_pk_mul_f32 v[72:73], v[72:73], v[150:151] op_sel_hi:[1,0]
	s_nop 0
	v_pk_mul_f32 v[80:81], v[76:77], s[98:99] op_sel_hi:[1,0]
	s_nop 0
	v_exp_f32_e32 v80, v80
	v_exp_f32_e32 v81, v81
	v_pk_mul_f32 v[72:73], v[76:77], v[72:73]
	v_pk_add_f32 v[80:81], v[80:81], 1.0 op_sel_hi:[1,0]
	s_nop 0
	v_rcp_f32_e32 v80, v80
	v_rcp_f32_e32 v81, v81
	v_pk_mul_f32 v[76:77], v[78:79], v[150:151] op_sel_hi:[1,0]
	v_pk_mul_f32 v[68:69], v[68:69], v[150:151] op_sel_hi:[1,0]
	v_pk_mul_f32 v[74:75], v[74:75], v[150:151] op_sel_hi:[1,0]
	v_mul_f32_e32 v79, 0xbfb8aa3b, v77
	v_pk_mul_f32 v[72:73], v[72:73], v[80:81]
	v_mul_f32_e32 v80, 0xbfb8aa3b, v68
	v_pk_mul_f32 v[74:75], v[76:77], v[74:75]
	v_mul_f32_e32 v77, 0xbfb8aa3b, v69
	v_pk_mul_f32 v[64:65], v[64:65], v[150:151] op_sel_hi:[1,0]
	v_exp_f32_e32 v80, v80
	v_exp_f32_e32 v77, v77
	v_pk_mul_f32 v[64:65], v[68:69], v[64:65]
	v_pk_mul_f32 v[68:69], v[70:71], v[150:151] op_sel_hi:[1,0]
	v_mul_f32_e32 v78, 0xbfb8aa3b, v76
	v_pk_mul_f32 v[70:71], v[68:69], s[98:99] op_sel_hi:[1,0]
	s_nop 0
	v_exp_f32_e32 v70, v70
	v_exp_f32_e32 v71, v71
	v_add_f32_e32 v76, 1.0, v80
	v_add_f32_e32 v77, 1.0, v77
	v_exp_f32_e32 v78, v78
	v_exp_f32_e32 v79, v79
	v_rcp_f32_e32 v76, v76
	v_rcp_f32_e32 v77, v77
	v_pk_add_f32 v[70:71], v[70:71], 1.0 op_sel_hi:[1,0]
	s_nop 0
	v_rcp_f32_e32 v70, v70
	v_rcp_f32_e32 v71, v71
	v_add_f32_e32 v78, 1.0, v78
	v_add_f32_e32 v79, 1.0, v79
	v_pk_mul_f32 v[76:77], v[64:65], v[76:77]
	v_pk_mul_f32 v[64:65], v[66:67], v[150:151] op_sel_hi:[1,0]
	v_rcp_f32_e32 v78, v78
	v_rcp_f32_e32 v79, v79
	v_pk_mul_f32 v[64:65], v[68:69], v[64:65]
	v_cvt_pk_bf16_f32 v66, v76, v77
	v_pk_mul_f32 v[68:69], v[64:65], v[70:71]
	v_add_u32_e32 v70, 48, v126
	v_cvt_pk_bf16_f32 v67, v68, v69
	v_mad_i64_i32 v[68:69], s[74:75], v70, s65, v[114:115]
	v_lshl_add_u64 v[68:69], v[68:69], 0, s[72:73]
	v_pk_mul_f32 v[74:75], v[74:75], v[78:79]
	v_lshl_add_u64 v[68:69], v[68:69], 0, s[48:49]
	v_cvt_pk_bf16_f32 v64, v72, v73
	v_cvt_pk_bf16_f32 v65, v74, v75
	v_pk_mul_f32 v[60:61], v[60:61], v[148:149] op_sel_hi:[1,0]
	v_lshl_add_u64 v[68:69], v[68:69], 0, v[110:111]
	global_store_dwordx4 v[68:69], v[64:67], off
	v_pk_mul_f32 v[56:57], v[56:57], v[148:149] op_sel_hi:[1,0]
	s_nop 0
	v_pk_mul_f32 v[64:65], v[60:61], s[98:99] op_sel_hi:[1,0]
	s_nop 0
	v_exp_f32_e32 v64, v64
	v_exp_f32_e32 v65, v65
	v_pk_mul_f32 v[56:57], v[60:61], v[56:57]
	v_pk_add_f32 v[64:65], v[64:65], 1.0 op_sel_hi:[1,0]
	s_nop 0
	v_rcp_f32_e32 v64, v64
	v_rcp_f32_e32 v65, v65
	v_pk_mul_f32 v[60:61], v[62:63], v[148:149] op_sel_hi:[1,0]
	v_pk_mul_f32 v[52:53], v[52:53], v[148:149] op_sel_hi:[1,0]
	v_pk_mul_f32 v[58:59], v[58:59], v[148:149] op_sel_hi:[1,0]
	v_mul_f32_e32 v63, 0xbfb8aa3b, v61
	v_pk_mul_f32 v[56:57], v[56:57], v[64:65]
	v_mul_f32_e32 v64, 0xbfb8aa3b, v52
	v_pk_mul_f32 v[58:59], v[60:61], v[58:59]
	v_mul_f32_e32 v61, 0xbfb8aa3b, v53
	v_pk_mul_f32 v[48:49], v[48:49], v[148:149] op_sel_hi:[1,0]
	v_exp_f32_e32 v64, v64
	v_exp_f32_e32 v61, v61
	v_pk_mul_f32 v[48:49], v[52:53], v[48:49]
	v_pk_mul_f32 v[52:53], v[54:55], v[148:149] op_sel_hi:[1,0]
	v_mul_f32_e32 v62, 0xbfb8aa3b, v60
	v_pk_mul_f32 v[54:55], v[52:53], s[98:99] op_sel_hi:[1,0]
	s_nop 0
	v_exp_f32_e32 v54, v54
	v_exp_f32_e32 v55, v55
	v_add_f32_e32 v60, 1.0, v64
	v_add_f32_e32 v61, 1.0, v61
	v_exp_f32_e32 v62, v62
	v_exp_f32_e32 v63, v63
	v_rcp_f32_e32 v60, v60
	v_rcp_f32_e32 v61, v61
	v_pk_add_f32 v[54:55], v[54:55], 1.0 op_sel_hi:[1,0]
	s_nop 0
	v_rcp_f32_e32 v54, v54
	v_rcp_f32_e32 v55, v55
	v_add_f32_e32 v62, 1.0, v62
	v_add_f32_e32 v63, 1.0, v63
	v_pk_mul_f32 v[60:61], v[48:49], v[60:61]
	v_pk_mul_f32 v[48:49], v[50:51], v[148:149] op_sel_hi:[1,0]
	v_fmamk_f32 v144, v144, 0x3a800000, v226
	v_rcp_f32_e32 v62, v62
	v_rcp_f32_e32 v63, v63
	v_pk_mul_f32 v[48:49], v[52:53], v[48:49]
	v_rsq_f32_e32 v146, v144
	v_add_u32_e32 v66, 0x80, v126
	v_pk_mul_f32 v[52:53], v[48:49], v[54:55]
	v_pk_mul_f32 v[58:59], v[58:59], v[62:63]
	v_cvt_pk_bf16_f32 v51, v52, v53
	v_mad_i64_i32 v[52:53], s[74:75], v66, s65, v[114:115]
	v_lshl_add_u64 v[52:53], v[52:53], 0, s[72:73]
	v_lshl_add_u64 v[52:53], v[52:53], 0, s[48:49]
	v_cvt_pk_bf16_f32 v48, v56, v57
	v_cvt_pk_bf16_f32 v49, v58, v59
	v_cvt_pk_bf16_f32 v50, v60, v61
	v_pk_mul_f32 v[44:45], v[44:45], v[146:147] op_sel_hi:[1,0]
	v_lshl_add_u64 v[52:53], v[52:53], 0, v[110:111]
	global_store_dwordx4 v[52:53], v[48:51], off
	v_pk_mul_f32 v[40:41], v[40:41], v[146:147] op_sel_hi:[1,0]
	s_nop 0
	v_pk_mul_f32 v[48:49], v[44:45], s[98:99] op_sel_hi:[1,0]
	s_nop 0
	v_exp_f32_e32 v48, v48
	v_exp_f32_e32 v49, v49
	v_pk_mul_f32 v[40:41], v[44:45], v[40:41]
	v_pk_add_f32 v[48:49], v[48:49], 1.0 op_sel_hi:[1,0]
	s_nop 0
	v_rcp_f32_e32 v48, v48
	v_rcp_f32_e32 v49, v49
	v_pk_mul_f32 v[44:45], v[46:47], v[146:147] op_sel_hi:[1,0]
	v_pk_mul_f32 v[36:37], v[36:37], v[146:147] op_sel_hi:[1,0]
	v_pk_mul_f32 v[42:43], v[42:43], v[146:147] op_sel_hi:[1,0]
	v_mul_f32_e32 v47, 0xbfb8aa3b, v45
	v_pk_mul_f32 v[40:41], v[40:41], v[48:49]
	v_mul_f32_e32 v48, 0xbfb8aa3b, v36
	v_pk_mul_f32 v[42:43], v[44:45], v[42:43]
	v_mul_f32_e32 v45, 0xbfb8aa3b, v37
	v_pk_mul_f32 v[32:33], v[32:33], v[146:147] op_sel_hi:[1,0]
	v_exp_f32_e32 v48, v48
	v_exp_f32_e32 v45, v45
	v_pk_mul_f32 v[32:33], v[36:37], v[32:33]
	v_pk_mul_f32 v[36:37], v[38:39], v[146:147] op_sel_hi:[1,0]
	v_mul_f32_e32 v46, 0xbfb8aa3b, v44
	v_pk_mul_f32 v[38:39], v[36:37], s[98:99] op_sel_hi:[1,0]
	s_nop 0
	v_exp_f32_e32 v38, v38
	v_exp_f32_e32 v39, v39
	v_add_f32_e32 v44, 1.0, v48
	v_add_f32_e32 v45, 1.0, v45
	v_exp_f32_e32 v46, v46
	v_exp_f32_e32 v47, v47
	v_rcp_f32_e32 v44, v44
	v_rcp_f32_e32 v45, v45
	v_pk_add_f32 v[38:39], v[38:39], 1.0 op_sel_hi:[1,0]
	s_nop 0
	v_rcp_f32_e32 v38, v38
	v_rcp_f32_e32 v39, v39
	v_add_f32_e32 v144, v145, v155
	v_add_f32_e32 v46, 1.0, v46
	v_add_f32_e32 v47, 1.0, v47
	v_pk_mul_f32 v[44:45], v[32:33], v[44:45]
	v_pk_mul_f32 v[32:33], v[34:35], v[146:147] op_sel_hi:[1,0]
	v_fmamk_f32 v144, v144, 0x3a800000, v226
	v_rcp_f32_e32 v46, v46
	v_rcp_f32_e32 v47, v47
	v_pk_mul_f32 v[32:33], v[36:37], v[32:33]
	v_rsq_f32_e32 v144, v144
	v_pk_mul_f32 v[36:37], v[32:33], v[38:39]
	v_add_u32_e32 v38, 0x90, v126
	v_cvt_pk_bf16_f32 v35, v36, v37
	v_mad_i64_i32 v[36:37], s[74:75], v38, s65, v[114:115]
	v_lshl_add_u64 v[36:37], v[36:37], 0, s[72:73]
	v_pk_mul_f32 v[42:43], v[42:43], v[46:47]
	v_lshl_add_u64 v[36:37], v[36:37], 0, s[48:49]
	v_cvt_pk_bf16_f32 v32, v40, v41
	v_cvt_pk_bf16_f32 v33, v42, v43
	v_cvt_pk_bf16_f32 v34, v44, v45
	v_pk_mul_f32 v[28:29], v[28:29], v[144:145] op_sel_hi:[1,0]
	v_lshl_add_u64 v[36:37], v[36:37], 0, v[110:111]
	global_store_dwordx4 v[36:37], v[32:35], off
	v_pk_mul_f32 v[24:25], v[24:25], v[144:145] op_sel_hi:[1,0]
	s_nop 0
	v_pk_mul_f32 v[32:33], v[28:29], s[98:99] op_sel_hi:[1,0]
	s_nop 0
	v_exp_f32_e32 v32, v32
	v_exp_f32_e32 v33, v33
	v_pk_mul_f32 v[24:25], v[28:29], v[24:25]
	v_pk_add_f32 v[32:33], v[32:33], 1.0 op_sel_hi:[1,0]
	s_nop 0
	v_rcp_f32_e32 v32, v32
	v_rcp_f32_e32 v33, v33
	v_pk_mul_f32 v[28:29], v[30:31], v[144:145] op_sel_hi:[1,0]
	v_pk_mul_f32 v[20:21], v[20:21], v[144:145] op_sel_hi:[1,0]
	v_pk_mul_f32 v[26:27], v[26:27], v[144:145] op_sel_hi:[1,0]
	v_mul_f32_e32 v31, 0xbfb8aa3b, v29
	v_pk_mul_f32 v[24:25], v[24:25], v[32:33]
	v_mul_f32_e32 v32, 0xbfb8aa3b, v20
	v_pk_mul_f32 v[26:27], v[28:29], v[26:27]
	v_mul_f32_e32 v29, 0xbfb8aa3b, v21
	v_pk_mul_f32 v[16:17], v[16:17], v[144:145] op_sel_hi:[1,0]
	v_exp_f32_e32 v32, v32
	v_exp_f32_e32 v29, v29
	v_pk_mul_f32 v[16:17], v[20:21], v[16:17]
	v_pk_mul_f32 v[20:21], v[22:23], v[144:145] op_sel_hi:[1,0]
	v_mul_f32_e32 v30, 0xbfb8aa3b, v28
	v_pk_mul_f32 v[22:23], v[20:21], s[98:99] op_sel_hi:[1,0]
	s_nop 0
	v_exp_f32_e32 v22, v22
	v_exp_f32_e32 v23, v23
	v_add_f32_e32 v28, 1.0, v32
	v_add_f32_e32 v29, 1.0, v29
	v_exp_f32_e32 v30, v30
	v_exp_f32_e32 v31, v31
	v_rcp_f32_e32 v28, v28
	v_rcp_f32_e32 v29, v29
	v_pk_add_f32 v[22:23], v[22:23], 1.0 op_sel_hi:[1,0]
	s_nop 0
	v_rcp_f32_e32 v22, v22
	v_rcp_f32_e32 v23, v23
	v_add_f32_e32 v30, 1.0, v30
	v_add_f32_e32 v31, 1.0, v31
	v_pk_mul_f32 v[28:29], v[16:17], v[28:29]
	v_pk_mul_f32 v[16:17], v[18:19], v[144:145] op_sel_hi:[1,0]
	v_fmamk_f32 v142, v142, 0x3a800000, v226
	v_rcp_f32_e32 v30, v30
	v_rcp_f32_e32 v31, v31
	v_pk_mul_f32 v[16:17], v[20:21], v[16:17]
	v_rsq_f32_e32 v142, v142
	v_pk_mul_f32 v[20:21], v[16:17], v[22:23]
	v_add_u32_e32 v22, 0xa0, v126
	v_cvt_pk_bf16_f32 v19, v20, v21
	v_mad_i64_i32 v[20:21], s[74:75], v22, s65, v[114:115]
	v_lshl_add_u64 v[20:21], v[20:21], 0, s[72:73]
	v_pk_mul_f32 v[26:27], v[26:27], v[30:31]
	v_lshl_add_u64 v[20:21], v[20:21], 0, s[48:49]
	v_cvt_pk_bf16_f32 v16, v24, v25
	v_cvt_pk_bf16_f32 v17, v26, v27
	v_cvt_pk_bf16_f32 v18, v28, v29
	v_pk_mul_f32 v[12:13], v[12:13], v[142:143] op_sel_hi:[1,0]
	v_lshl_add_u64 v[20:21], v[20:21], 0, v[110:111]
	global_store_dwordx4 v[20:21], v[16:19], off
	v_pk_mul_f32 v[8:9], v[8:9], v[142:143] op_sel_hi:[1,0]
	s_nop 0
	v_pk_mul_f32 v[16:17], v[12:13], s[98:99] op_sel_hi:[1,0]
	s_nop 0
	v_exp_f32_e32 v16, v16
	v_exp_f32_e32 v17, v17
	v_pk_mul_f32 v[8:9], v[12:13], v[8:9]
	v_pk_add_f32 v[16:17], v[16:17], 1.0 op_sel_hi:[1,0]
	s_nop 0
	v_rcp_f32_e32 v16, v16
	v_rcp_f32_e32 v17, v17
	v_pk_mul_f32 v[12:13], v[14:15], v[142:143] op_sel_hi:[1,0]
	v_pk_mul_f32 v[4:5], v[4:5], v[142:143] op_sel_hi:[1,0]
	v_pk_mul_f32 v[10:11], v[10:11], v[142:143] op_sel_hi:[1,0]
	v_mul_f32_e32 v15, 0xbfb8aa3b, v13
	v_pk_mul_f32 v[8:9], v[8:9], v[16:17]
	v_mul_f32_e32 v16, 0xbfb8aa3b, v4
	v_pk_mul_f32 v[10:11], v[12:13], v[10:11]
	v_mul_f32_e32 v13, 0xbfb8aa3b, v5
	v_pk_mul_f32 v[0:1], v[0:1], v[142:143] op_sel_hi:[1,0]
	v_exp_f32_e32 v16, v16
	v_exp_f32_e32 v13, v13
	v_pk_mul_f32 v[0:1], v[4:5], v[0:1]
	v_pk_mul_f32 v[4:5], v[6:7], v[142:143] op_sel_hi:[1,0]
	v_mul_f32_e32 v14, 0xbfb8aa3b, v12
	v_pk_mul_f32 v[6:7], v[4:5], s[98:99] op_sel_hi:[1,0]
	s_nop 0
	v_exp_f32_e32 v6, v6
	v_exp_f32_e32 v7, v7
	v_add_f32_e32 v12, 1.0, v16
	v_add_f32_e32 v13, 1.0, v13
	v_exp_f32_e32 v14, v14
	v_exp_f32_e32 v15, v15
	v_rcp_f32_e32 v12, v12
	v_rcp_f32_e32 v13, v13
	v_pk_add_f32 v[6:7], v[6:7], 1.0 op_sel_hi:[1,0]
	s_nop 0
	v_rcp_f32_e32 v6, v6
	v_rcp_f32_e32 v7, v7
	v_add_f32_e32 v14, 1.0, v14
	v_add_f32_e32 v15, 1.0, v15
	v_pk_mul_f32 v[12:13], v[0:1], v[12:13]
	v_pk_mul_f32 v[0:1], v[2:3], v[142:143] op_sel_hi:[1,0]
	v_rcp_f32_e32 v14, v14
	v_rcp_f32_e32 v15, v15
	v_pk_mul_f32 v[0:1], v[4:5], v[0:1]
	v_cvt_pk_bf16_f32 v2, v12, v13
	v_pk_mul_f32 v[4:5], v[0:1], v[6:7]
	v_add_u32_e32 v6, 0xb0, v126
	v_cvt_pk_bf16_f32 v3, v4, v5
	v_mad_i64_i32 v[4:5], s[74:75], v6, s65, v[114:115]
	v_lshl_add_u64 v[4:5], v[4:5], 0, s[72:73]
	v_pk_mul_f32 v[10:11], v[10:11], v[14:15]
	v_lshl_add_u64 v[4:5], v[4:5], 0, s[48:49]
	v_cvt_pk_bf16_f32 v0, v8, v9
	v_cvt_pk_bf16_f32 v1, v10, v11
	v_lshl_add_u64 v[4:5], v[4:5], 0, v[110:111]
	s_mov_b64 s[6:7], -1
	global_store_dwordx4 v[4:5], v[0:3], off
	s_cbranch_vccnz .LBB0_151
	s_andn2_b64 vcc, exec, s[52:53]
	s_cbranch_vccnz .LBB0_150
	s_barrier
	s_branch .LBB0_150

.LBB0_1930:
	s_mov_b32 s98, 0xbfb8aa3b
	v_mov_b32_e32 v180, v147
	v_mov_b32_e32 v142, v149
	s_add_i32 s22, 0, 0x21000
	v_add_u32_e32 v181, s86, v142
	v_lshlrev_b32_e32 v142, 4, v180
	v_lshlrev_b32_e32 v143, 6, v181
	s_waitcnt vmcnt(16)
	s_barrier
	v_add3_u32 v146, s22, v142, v143
	ds_read_b128 v[142:145], v146
	ds_read_b128 v[154:157], v146 offset:1024
	ds_read_b128 v[158:161], v146 offset:2048
	ds_read_b128 v[162:165], v146 offset:3072
	v_and_b32_e32 v150, 64, v225
	v_xor_b32_e32 v148, 16, v225
	v_add_u32_e32 v150, 64, v150
	v_cmp_lt_i32_e32 vcc, v148, v150
	s_waitcnt lgkmcnt(0)
	v_mov_b32_e32 v166, v143
	v_mov_b32_e32 v167, v144
	v_mov_b32_e32 v143, v145
	v_cndmask_b32_e32 v148, v225, v148, vcc
	v_pk_add_f32 v[142:143], v[166:167], v[142:143]
	v_lshlrev_b32_e32 v182, 2, v148
	v_add_f32_e32 v142, v142, v143
	ds_bpermute_b32 v143, v182, v142
	v_xor_b32_e32 v144, 32, v225
	v_cmp_lt_i32_e32 vcc, v144, v150
	v_mov_b32_e32 v178, v155
	v_mov_b32_e32 v179, v156
	v_cndmask_b32_e32 v144, v225, v144, vcc
	v_lshlrev_b32_e32 v183, 2, v144
	s_waitcnt lgkmcnt(0)
	v_add_f32_e32 v148, v142, v143
	ds_bpermute_b32 v150, v183, v148
	v_mov_b32_e32 v155, v157
	v_pk_add_f32 v[154:155], v[178:179], v[154:155]
	ds_read_b128 v[142:145], v146 offset:8192
	ds_read_b128 v[166:169], v146 offset:9216
	ds_read_b128 v[170:173], v146 offset:10240
	ds_read_b128 v[174:177], v146 offset:11264
	s_and_b64 vcc, exec, s[6:7]
	s_waitcnt lgkmcnt(0)
	v_add_f32_e32 v146, v148, v150
	v_add_f32_e32 v148, v154, v155
	v_mov_b32_e32 v154, v159
	v_mov_b32_e32 v155, v160
	v_mov_b32_e32 v159, v161
	v_pk_add_f32 v[154:155], v[154:155], v[158:159]
	ds_bpermute_b32 v150, v182, v148
	v_add_f32_e32 v152, v154, v155
	ds_bpermute_b32 v154, v182, v152
	v_fmamk_f32 v146, v146, 0x3a800000, v226
	v_rsq_f32_e32 v156, v146
	s_waitcnt lgkmcnt(0)
	v_add_f32_e32 v146, v148, v150
	v_mov_b32_e32 v155, v164
	v_add_f32_e32 v150, v152, v154
	v_mov_b32_e32 v154, v163
	v_mov_b32_e32 v163, v165
	v_pk_add_f32 v[154:155], v[154:155], v[162:163]
	ds_bpermute_b32 v148, v183, v146
	v_add_f32_e32 v155, v154, v155
	v_mov_b32_e32 v158, v143
	v_mov_b32_e32 v159, v144
	v_mov_b32_e32 v143, v145
	ds_bpermute_b32 v157, v182, v155
	v_pk_add_f32 v[142:143], v[158:159], v[142:143]
	ds_bpermute_b32 v152, v183, v150
	v_add_f32_e32 v142, v142, v143
	ds_bpermute_b32 v143, v182, v142
	s_waitcnt lgkmcnt(0)
	v_add_f32_e32 v146, v146, v148
	v_fmamk_f32 v146, v146, 0x3a800000, v226
	v_add_f32_e32 v148, v155, v157
	v_rsq_f32_e32 v154, v146
	v_add_f32_e32 v146, v150, v152
	ds_bpermute_b32 v150, v183, v148
	v_add_f32_e32 v145, v142, v143
	v_mov_b32_e32 v142, v167
	v_mov_b32_e32 v143, v168
	v_mov_b32_e32 v167, v169
	v_fmamk_f32 v144, v146, 0x3a800000, v226
	ds_bpermute_b32 v146, v183, v145
	v_pk_add_f32 v[142:143], v[142:143], v[166:167]
	v_rsq_f32_e32 v152, v144
	v_add_f32_e32 v142, v142, v143
	ds_bpermute_b32 v143, v182, v142
	s_waitcnt lgkmcnt(0)
	v_add_f32_e32 v144, v148, v150
	v_fmamk_f32 v144, v144, 0x3a800000, v226
	v_rsq_f32_e32 v150, v144
	v_add_f32_e32 v144, v145, v146
	v_fmamk_f32 v144, v144, 0x3a800000, v226
	v_rsq_f32_e32 v148, v144
	v_add_f32_e32 v144, v142, v143
	v_mov_b32_e32 v142, v171
	v_mov_b32_e32 v143, v172
	v_mov_b32_e32 v171, v173
	v_pk_add_f32 v[142:143], v[142:143], v[170:171]
	v_pk_mul_f32 v[158:159], v[126:127], v[156:157] op_sel_hi:[1,0]
	v_add_f32_e32 v146, v142, v143
	v_mov_b32_e32 v142, v175
	v_mov_b32_e32 v143, v176
	v_mov_b32_e32 v175, v177
	v_pk_add_f32 v[142:143], v[142:143], v[174:175]
	v_add_f32_e32 v142, v142, v143
	ds_bpermute_b32 v143, v182, v142
	v_pk_mul_f32 v[128:129], v[128:129], v[156:157] op_sel_hi:[1,0]
	v_pk_mul_f32 v[122:123], v[122:123], v[156:157] op_sel_hi:[1,0]
	v_pk_mul_f32 v[118:119], v[118:119], v[156:157] op_sel_hi:[1,0]
	s_waitcnt lgkmcnt(0)
	v_add_f32_e32 v142, v142, v143
	ds_bpermute_b32 v143, v183, v142
	v_pk_mul_f32 v[122:123], v[158:159], v[122:123]
	v_pk_mul_f32 v[124:125], v[124:125], v[156:157] op_sel_hi:[1,0]
	s_waitcnt lgkmcnt(0)
	v_add_f32_e32 v142, v142, v143
	v_pk_mul_f32 v[162:163], v[158:159], s[98:99] op_sel_hi:[1,0]
	s_nop 0
	v_exp_f32_e32 v162, v162
	v_exp_f32_e32 v163, v163
	v_pk_mul_f32 v[114:115], v[114:115], v[156:157] op_sel_hi:[1,0]
	v_pk_mul_f32 v[124:125], v[128:129], v[124:125]
	v_pk_mul_f32 v[114:115], v[118:119], v[114:115]
	v_pk_add_f32 v[162:163], v[162:163], 1.0 op_sel_hi:[1,0]
	s_nop 0
	v_rcp_f32_e32 v162, v162
	v_rcp_f32_e32 v163, v163
	v_mul_f32_e32 v127, 0xbfb8aa3b, v128
	v_exp_f32_e32 v127, v127
	v_mul_f32_e32 v143, 0xbfb8aa3b, v129
	v_exp_f32_e32 v143, v143
	v_add_f32_e32 v127, 1.0, v127
	v_rcp_f32_e32 v158, v127
	v_add_f32_e32 v127, 1.0, v143
	v_rcp_f32_e32 v159, v127
	v_pk_mul_f32 v[128:129], v[118:119], s[98:99] op_sel_hi:[1,0]
	s_nop 0
	v_exp_f32_e32 v128, v128
	v_pk_mul_f32 v[118:119], v[120:121], v[156:157] op_sel_hi:[1,0]
	v_exp_f32_e32 v129, v129
	v_pk_mul_f32 v[120:121], v[118:119], s[98:99] op_sel_hi:[1,0]
	s_nop 0
	v_exp_f32_e32 v120, v120
	v_exp_f32_e32 v121, v121
	ds_bpermute_b32 v145, v183, v144
	ds_bpermute_b32 v155, v182, v146
	v_pk_add_f32 v[128:129], v[128:129], 1.0 op_sel_hi:[1,0]
	s_nop 0
	v_rcp_f32_e32 v128, v128
	v_rcp_f32_e32 v129, v129
	v_pk_add_f32 v[120:121], v[120:121], 1.0 op_sel_hi:[1,0]
	s_nop 0
	v_rcp_f32_e32 v120, v120
	v_rcp_f32_e32 v121, v121
	s_waitcnt lgkmcnt(0)
	v_add_f32_e32 v144, v144, v145
	v_add_f32_e32 v145, v146, v155
	v_pk_mul_f32 v[116:117], v[116:117], v[156:157] op_sel_hi:[1,0]
	ds_bpermute_b32 v155, v183, v145
	v_pk_mul_f32 v[114:115], v[114:115], v[128:129]
	v_pk_mul_f32 v[116:117], v[118:119], v[116:117]
	v_lshl_add_u32 v126, s68, 8, v181
	v_pk_mul_f32 v[120:121], v[116:117], v[120:121]
	v_cvt_pk_bf16_f32 v118, v114, v115
	v_mov_b64_e32 v[114:115], s[50:51]
	v_cvt_pk_bf16_f32 v119, v120, v121
	v_mad_i64_i32 v[120:121], s[22:23], v126, s65, v[114:115]
	s_lshl_b32 s22, s93, 7
	v_pk_mul_f32 v[122:123], v[122:123], v[162:163]
	s_ashr_i32 s23, s22, 31
	v_lshlrev_b32_e32 v160, 3, v180
	v_cvt_pk_bf16_f32 v116, v122, v123
	s_lshl_b64 s[68:69], s[22:23], 1
	s_waitcnt lgkmcnt(0)
	v_pk_mul_f32 v[122:123], v[110:111], v[154:155] op_sel_hi:[1,0]
	v_ashrrev_i32_e32 v161, 31, v160
	v_pk_mul_f32 v[124:125], v[124:125], v[158:159]
	v_lshl_add_u64 v[120:121], v[120:121], 0, s[68:69]
	v_cvt_pk_bf16_f32 v117, v124, v125
	v_lshl_add_u64 v[120:121], v[120:121], 0, s[48:49]
	v_lshlrev_b64 v[110:111], 1, v[160:161]
	v_lshl_add_u64 v[120:121], v[120:121], 0, v[110:111]
	global_store_dwordx4 v[120:121], v[116:119], off
	v_pk_mul_f32 v[112:113], v[112:113], v[154:155] op_sel_hi:[1,0]
	v_pk_mul_f32 v[106:107], v[106:107], v[154:155] op_sel_hi:[1,0]
	v_pk_mul_f32 v[116:117], v[122:123], s[98:99] op_sel_hi:[1,0]
	s_nop 0
	v_exp_f32_e32 v116, v116
	v_exp_f32_e32 v117, v117
	v_mul_f32_e32 v118, 0xbfb8aa3b, v112
	v_pk_add_f32 v[116:117], v[116:117], 1.0 op_sel_hi:[1,0]
	s_nop 0
	v_rcp_f32_e32 v116, v116
	v_rcp_f32_e32 v117, v117
	v_exp_f32_e32 v118, v118
	v_pk_mul_f32 v[106:107], v[122:123], v[106:107]
	v_pk_mul_f32 v[102:103], v[102:103], v[154:155] op_sel_hi:[1,0]
	v_pk_mul_f32 v[108:109], v[108:109], v[154:155] op_sel_hi:[1,0]
	v_mul_f32_e32 v119, 0xbfb8aa3b, v113
	v_pk_mul_f32 v[106:107], v[106:107], v[116:117]
	v_add_f32_e32 v116, 1.0, v118
	v_pk_mul_f32 v[108:109], v[112:113], v[108:109]
	v_pk_mul_f32 v[112:113], v[102:103], s[98:99] op_sel_hi:[1,0]
	v_pk_mul_f32 v[98:99], v[98:99], v[154:155] op_sel_hi:[1,0]
	v_exp_f32_e32 v112, v112
	v_exp_f32_e32 v113, v113
	v_pk_mul_f32 v[98:99], v[102:103], v[98:99]
	v_pk_mul_f32 v[102:103], v[104:105], v[154:155] op_sel_hi:[1,0]
	v_pk_mul_f32 v[104:105], v[102:103], s[98:99] op_sel_hi:[1,0]
	s_nop 0
	v_exp_f32_e32 v104, v104
	v_exp_f32_e32 v105, v105
	v_pk_add_f32 v[112:113], v[112:113], 1.0 op_sel_hi:[1,0]
	v_exp_f32_e32 v119, v119
	v_rcp_f32_e32 v112, v112
	v_rcp_f32_e32 v113, v113
	v_pk_add_f32 v[104:105], v[104:105], 1.0 op_sel_hi:[1,0]
	s_nop 0
	v_rcp_f32_e32 v104, v104
	v_rcp_f32_e32 v105, v105
	v_add_f32_e32 v117, 1.0, v119
	v_pk_mul_f32 v[112:113], v[98:99], v[112:113]
	v_pk_mul_f32 v[98:99], v[100:101], v[154:155] op_sel_hi:[1,0]
	v_rcp_f32_e32 v116, v116
	v_rcp_f32_e32 v117, v117
	v_pk_mul_f32 v[98:99], v[102:103], v[98:99]
	v_cvt_pk_bf16_f32 v100, v112, v113
	v_pk_mul_f32 v[102:103], v[98:99], v[104:105]
	v_add_u32_e32 v104, 16, v126
	v_cvt_pk_bf16_f32 v101, v102, v103
	v_mad_i64_i32 v[102:103], s[22:23], v104, s65, v[114:115]
	v_lshl_add_u64 v[102:103], v[102:103], 0, s[68:69]
	v_pk_mul_f32 v[108:109], v[108:109], v[116:117]
	v_lshl_add_u64 v[102:103], v[102:103], 0, s[48:49]
	v_cvt_pk_bf16_f32 v98, v106, v107
	v_cvt_pk_bf16_f32 v99, v108, v109
	v_pk_mul_f32 v[92:93], v[92:93], v[152:153] op_sel_hi:[1,0]
	v_lshl_add_u64 v[102:103], v[102:103], 0, v[110:111]
	global_store_dwordx4 v[102:103], v[98:101], off
	v_pk_mul_f32 v[88:89], v[88:89], v[152:153] op_sel_hi:[1,0]
	s_nop 0
	v_pk_mul_f32 v[98:99], v[92:93], s[98:99] op_sel_hi:[1,0]
	s_nop 0
	v_exp_f32_e32 v98, v98
	v_exp_f32_e32 v99, v99
	v_pk_mul_f32 v[88:89], v[92:93], v[88:89]
	v_pk_add_f32 v[98:99], v[98:99], 1.0 op_sel_hi:[1,0]
	s_nop 0
	v_rcp_f32_e32 v98, v98
	v_rcp_f32_e32 v99, v99
	v_pk_mul_f32 v[92:93], v[94:95], v[152:153] op_sel_hi:[1,0]
	v_pk_mul_f32 v[84:85], v[84:85], v[152:153] op_sel_hi:[1,0]
	v_pk_mul_f32 v[90:91], v[90:91], v[152:153] op_sel_hi:[1,0]
	v_mul_f32_e32 v95, 0xbfb8aa3b, v93
	v_pk_mul_f32 v[88:89], v[88:89], v[98:99]
	v_mul_f32_e32 v98, 0xbfb8aa3b, v84
	v_pk_mul_f32 v[90:91], v[92:93], v[90:91]
	v_mul_f32_e32 v93, 0xbfb8aa3b, v85
	v_pk_mul_f32 v[80:81], v[80:81], v[152:153] op_sel_hi:[1,0]
	v_exp_f32_e32 v98, v98
	v_exp_f32_e32 v93, v93
	v_pk_mul_f32 v[80:81], v[84:85], v[80:81]
	v_pk_mul_f32 v[84:85], v[86:87], v[152:153] op_sel_hi:[1,0]
	v_mul_f32_e32 v94, 0xbfb8aa3b, v92
	v_pk_mul_f32 v[86:87], v[84:85], s[98:99] op_sel_hi:[1,0]
	s_nop 0
	v_exp_f32_e32 v86, v86
	v_exp_f32_e32 v87, v87
	v_add_f32_e32 v92, 1.0, v98
	v_add_f32_e32 v93, 1.0, v93
	v_exp_f32_e32 v94, v94
	v_exp_f32_e32 v95, v95
	v_rcp_f32_e32 v92, v92
	v_rcp_f32_e32 v93, v93
	v_pk_add_f32 v[86:87], v[86:87], 1.0 op_sel_hi:[1,0]
	s_nop 0
	v_rcp_f32_e32 v86, v86
	v_rcp_f32_e32 v87, v87
	v_add_f32_e32 v94, 1.0, v94
	v_add_f32_e32 v95, 1.0, v95
	v_pk_mul_f32 v[92:93], v[80:81], v[92:93]
	v_pk_mul_f32 v[80:81], v[82:83], v[152:153] op_sel_hi:[1,0]
	v_rcp_f32_e32 v94, v94
	v_rcp_f32_e32 v95, v95
	v_pk_mul_f32 v[80:81], v[84:85], v[80:81]
	v_cvt_pk_bf16_f32 v82, v92, v93
	v_pk_mul_f32 v[84:85], v[80:81], v[86:87]
	v_add_u32_e32 v86, 32, v126
	v_cvt_pk_bf16_f32 v83, v84, v85
	v_mad_i64_i32 v[84:85], s[22:23], v86, s65, v[114:115]
	v_lshl_add_u64 v[84:85], v[84:85], 0, s[68:69]
	v_pk_mul_f32 v[90:91], v[90:91], v[94:95]
	v_lshl_add_u64 v[84:85], v[84:85], 0, s[48:49]
	v_cvt_pk_bf16_f32 v80, v88, v89
	v_cvt_pk_bf16_f32 v81, v90, v91
	v_pk_mul_f32 v[76:77], v[76:77], v[150:151] op_sel_hi:[1,0]
	v_lshl_add_u64 v[84:85], v[84:85], 0, v[110:111]
	global_store_dwordx4 v[84:85], v[80:83], off
	v_pk_mul_f32 v[72:73], v[72:73], v[150:151] op_sel_hi:[1,0]
	s_nop 0
	v_pk_mul_f32 v[80:81], v[76:77], s[98:99] op_sel_hi:[1,0]
	s_nop 0
	v_exp_f32_e32 v80, v80
	v_exp_f32_e32 v81, v81
	v_pk_mul_f32 v[72:73], v[76:77], v[72:73]
	v_pk_add_f32 v[80:81], v[80:81], 1.0 op_sel_hi:[1,0]
	s_nop 0
	v_rcp_f32_e32 v80, v80
	v_rcp_f32_e32 v81, v81
	v_pk_mul_f32 v[76:77], v[78:79], v[150:151] op_sel_hi:[1,0]
	v_pk_mul_f32 v[68:69], v[68:69], v[150:151] op_sel_hi:[1,0]
	v_pk_mul_f32 v[74:75], v[74:75], v[150:151] op_sel_hi:[1,0]
	v_mul_f32_e32 v79, 0xbfb8aa3b, v77
	v_pk_mul_f32 v[72:73], v[72:73], v[80:81]
	v_mul_f32_e32 v80, 0xbfb8aa3b, v68
	v_pk_mul_f32 v[74:75], v[76:77], v[74:75]
	v_mul_f32_e32 v77, 0xbfb8aa3b, v69
	v_pk_mul_f32 v[64:65], v[64:65], v[150:151] op_sel_hi:[1,0]
	v_exp_f32_e32 v80, v80
	v_exp_f32_e32 v77, v77
	v_pk_mul_f32 v[64:65], v[68:69], v[64:65]
	v_pk_mul_f32 v[68:69], v[70:71], v[150:151] op_sel_hi:[1,0]
	v_mul_f32_e32 v78, 0xbfb8aa3b, v76
	v_pk_mul_f32 v[70:71], v[68:69], s[98:99] op_sel_hi:[1,0]
	s_nop 0
	v_exp_f32_e32 v70, v70
	v_exp_f32_e32 v71, v71
	v_add_f32_e32 v76, 1.0, v80
	v_add_f32_e32 v77, 1.0, v77
	v_exp_f32_e32 v78, v78
	v_exp_f32_e32 v79, v79
	v_rcp_f32_e32 v76, v76
	v_rcp_f32_e32 v77, v77
	v_pk_add_f32 v[70:71], v[70:71], 1.0 op_sel_hi:[1,0]
	s_nop 0
	v_rcp_f32_e32 v70, v70
	v_rcp_f32_e32 v71, v71
	v_add_f32_e32 v78, 1.0, v78
	v_add_f32_e32 v79, 1.0, v79
	v_pk_mul_f32 v[76:77], v[64:65], v[76:77]
	v_pk_mul_f32 v[64:65], v[66:67], v[150:151] op_sel_hi:[1,0]
	v_rcp_f32_e32 v78, v78
	v_rcp_f32_e32 v79, v79
	v_pk_mul_f32 v[64:65], v[68:69], v[64:65]
	v_cvt_pk_bf16_f32 v66, v76, v77
	v_pk_mul_f32 v[68:69], v[64:65], v[70:71]
	v_add_u32_e32 v70, 48, v126
	v_cvt_pk_bf16_f32 v67, v68, v69
	v_mad_i64_i32 v[68:69], s[22:23], v70, s65, v[114:115]
	v_lshl_add_u64 v[68:69], v[68:69], 0, s[68:69]
	v_pk_mul_f32 v[74:75], v[74:75], v[78:79]
	v_lshl_add_u64 v[68:69], v[68:69], 0, s[48:49]
	v_cvt_pk_bf16_f32 v64, v72, v73
	v_cvt_pk_bf16_f32 v65, v74, v75
	v_pk_mul_f32 v[60:61], v[60:61], v[148:149] op_sel_hi:[1,0]
	v_lshl_add_u64 v[68:69], v[68:69], 0, v[110:111]
	global_store_dwordx4 v[68:69], v[64:67], off
	v_pk_mul_f32 v[56:57], v[56:57], v[148:149] op_sel_hi:[1,0]
	s_nop 0
	v_pk_mul_f32 v[64:65], v[60:61], s[98:99] op_sel_hi:[1,0]
	s_nop 0
	v_exp_f32_e32 v64, v64
	v_exp_f32_e32 v65, v65
	v_pk_mul_f32 v[56:57], v[60:61], v[56:57]
	v_pk_add_f32 v[64:65], v[64:65], 1.0 op_sel_hi:[1,0]
	s_nop 0
	v_rcp_f32_e32 v64, v64
	v_rcp_f32_e32 v65, v65
	v_pk_mul_f32 v[60:61], v[62:63], v[148:149] op_sel_hi:[1,0]
	v_pk_mul_f32 v[52:53], v[52:53], v[148:149] op_sel_hi:[1,0]
	v_pk_mul_f32 v[58:59], v[58:59], v[148:149] op_sel_hi:[1,0]
	v_mul_f32_e32 v63, 0xbfb8aa3b, v61
	v_pk_mul_f32 v[56:57], v[56:57], v[64:65]
	v_mul_f32_e32 v64, 0xbfb8aa3b, v52
	v_pk_mul_f32 v[58:59], v[60:61], v[58:59]
	v_mul_f32_e32 v61, 0xbfb8aa3b, v53
	v_pk_mul_f32 v[48:49], v[48:49], v[148:149] op_sel_hi:[1,0]
	v_exp_f32_e32 v64, v64
	v_exp_f32_e32 v61, v61
	v_pk_mul_f32 v[48:49], v[52:53], v[48:49]
	v_pk_mul_f32 v[52:53], v[54:55], v[148:149] op_sel_hi:[1,0]
	v_mul_f32_e32 v62, 0xbfb8aa3b, v60
	v_pk_mul_f32 v[54:55], v[52:53], s[98:99] op_sel_hi:[1,0]
	s_nop 0
	v_exp_f32_e32 v54, v54
	v_exp_f32_e32 v55, v55
	v_add_f32_e32 v60, 1.0, v64
	v_add_f32_e32 v61, 1.0, v61
	v_exp_f32_e32 v62, v62
	v_exp_f32_e32 v63, v63
	v_rcp_f32_e32 v60, v60
	v_rcp_f32_e32 v61, v61
	v_pk_add_f32 v[54:55], v[54:55], 1.0 op_sel_hi:[1,0]
	s_nop 0
	v_rcp_f32_e32 v54, v54
	v_rcp_f32_e32 v55, v55
	v_add_f32_e32 v62, 1.0, v62
	v_add_f32_e32 v63, 1.0, v63
	v_pk_mul_f32 v[60:61], v[48:49], v[60:61]
	v_pk_mul_f32 v[48:49], v[50:51], v[148:149] op_sel_hi:[1,0]
	v_fmamk_f32 v144, v144, 0x3a800000, v226
	v_rcp_f32_e32 v62, v62
	v_rcp_f32_e32 v63, v63
	v_pk_mul_f32 v[48:49], v[52:53], v[48:49]
	v_rsq_f32_e32 v146, v144
	v_add_u32_e32 v66, 0x80, v126
	v_pk_mul_f32 v[52:53], v[48:49], v[54:55]
	v_pk_mul_f32 v[58:59], v[58:59], v[62:63]
	v_cvt_pk_bf16_f32 v51, v52, v53
	v_mad_i64_i32 v[52:53], s[22:23], v66, s65, v[114:115]
	v_lshl_add_u64 v[52:53], v[52:53], 0, s[68:69]
	v_lshl_add_u64 v[52:53], v[52:53], 0, s[48:49]
	v_cvt_pk_bf16_f32 v48, v56, v57
	v_cvt_pk_bf16_f32 v49, v58, v59
	v_cvt_pk_bf16_f32 v50, v60, v61
	v_pk_mul_f32 v[44:45], v[44:45], v[146:147] op_sel_hi:[1,0]
	v_lshl_add_u64 v[52:53], v[52:53], 0, v[110:111]
	global_store_dwordx4 v[52:53], v[48:51], off
	v_pk_mul_f32 v[40:41], v[40:41], v[146:147] op_sel_hi:[1,0]
	s_nop 0
	v_pk_mul_f32 v[48:49], v[44:45], s[98:99] op_sel_hi:[1,0]
	s_nop 0
	v_exp_f32_e32 v48, v48
	v_exp_f32_e32 v49, v49
	v_pk_mul_f32 v[40:41], v[44:45], v[40:41]
	v_pk_add_f32 v[48:49], v[48:49], 1.0 op_sel_hi:[1,0]
	s_nop 0
	v_rcp_f32_e32 v48, v48
	v_rcp_f32_e32 v49, v49
	v_pk_mul_f32 v[44:45], v[46:47], v[146:147] op_sel_hi:[1,0]
	v_pk_mul_f32 v[36:37], v[36:37], v[146:147] op_sel_hi:[1,0]
	v_pk_mul_f32 v[42:43], v[42:43], v[146:147] op_sel_hi:[1,0]
	v_mul_f32_e32 v47, 0xbfb8aa3b, v45
	v_pk_mul_f32 v[40:41], v[40:41], v[48:49]
	v_mul_f32_e32 v48, 0xbfb8aa3b, v36
	v_pk_mul_f32 v[42:43], v[44:45], v[42:43]
	v_mul_f32_e32 v45, 0xbfb8aa3b, v37
	v_pk_mul_f32 v[32:33], v[32:33], v[146:147] op_sel_hi:[1,0]
	v_exp_f32_e32 v48, v48
	v_exp_f32_e32 v45, v45
	v_pk_mul_f32 v[32:33], v[36:37], v[32:33]
	v_pk_mul_f32 v[36:37], v[38:39], v[146:147] op_sel_hi:[1,0]
	v_mul_f32_e32 v46, 0xbfb8aa3b, v44
	v_pk_mul_f32 v[38:39], v[36:37], s[98:99] op_sel_hi:[1,0]
	s_nop 0
	v_exp_f32_e32 v38, v38
	v_exp_f32_e32 v39, v39
	v_add_f32_e32 v44, 1.0, v48
	v_add_f32_e32 v45, 1.0, v45
	v_exp_f32_e32 v46, v46
	v_exp_f32_e32 v47, v47
	v_rcp_f32_e32 v44, v44
	v_rcp_f32_e32 v45, v45
	v_pk_add_f32 v[38:39], v[38:39], 1.0 op_sel_hi:[1,0]
	s_nop 0
	v_rcp_f32_e32 v38, v38
	v_rcp_f32_e32 v39, v39
	v_add_f32_e32 v144, v145, v155
	v_add_f32_e32 v46, 1.0, v46
	v_add_f32_e32 v47, 1.0, v47
	v_pk_mul_f32 v[44:45], v[32:33], v[44:45]
	v_pk_mul_f32 v[32:33], v[34:35], v[146:147] op_sel_hi:[1,0]
	v_fmamk_f32 v144, v144, 0x3a800000, v226
	v_rcp_f32_e32 v46, v46
	v_rcp_f32_e32 v47, v47
	v_pk_mul_f32 v[32:33], v[36:37], v[32:33]
	v_rsq_f32_e32 v144, v144
	v_pk_mul_f32 v[36:37], v[32:33], v[38:39]
	v_add_u32_e32 v38, 0x90, v126
	v_cvt_pk_bf16_f32 v35, v36, v37
	v_mad_i64_i32 v[36:37], s[22:23], v38, s65, v[114:115]
	v_lshl_add_u64 v[36:37], v[36:37], 0, s[68:69]
	v_pk_mul_f32 v[42:43], v[42:43], v[46:47]
	v_lshl_add_u64 v[36:37], v[36:37], 0, s[48:49]
	v_cvt_pk_bf16_f32 v32, v40, v41
	v_cvt_pk_bf16_f32 v33, v42, v43
	v_cvt_pk_bf16_f32 v34, v44, v45
	v_pk_mul_f32 v[28:29], v[28:29], v[144:145] op_sel_hi:[1,0]
	v_lshl_add_u64 v[36:37], v[36:37], 0, v[110:111]
	global_store_dwordx4 v[36:37], v[32:35], off
	v_pk_mul_f32 v[24:25], v[24:25], v[144:145] op_sel_hi:[1,0]
	s_nop 0
	v_pk_mul_f32 v[32:33], v[28:29], s[98:99] op_sel_hi:[1,0]
	s_nop 0
	v_exp_f32_e32 v32, v32
	v_exp_f32_e32 v33, v33
	v_pk_mul_f32 v[24:25], v[28:29], v[24:25]
	v_pk_add_f32 v[32:33], v[32:33], 1.0 op_sel_hi:[1,0]
	s_nop 0
	v_rcp_f32_e32 v32, v32
	v_rcp_f32_e32 v33, v33
	v_pk_mul_f32 v[28:29], v[30:31], v[144:145] op_sel_hi:[1,0]
	v_pk_mul_f32 v[20:21], v[20:21], v[144:145] op_sel_hi:[1,0]
	v_pk_mul_f32 v[26:27], v[26:27], v[144:145] op_sel_hi:[1,0]
	v_mul_f32_e32 v31, 0xbfb8aa3b, v29
	v_pk_mul_f32 v[24:25], v[24:25], v[32:33]
	v_mul_f32_e32 v32, 0xbfb8aa3b, v20
	v_pk_mul_f32 v[26:27], v[28:29], v[26:27]
	v_mul_f32_e32 v29, 0xbfb8aa3b, v21
	v_pk_mul_f32 v[16:17], v[16:17], v[144:145] op_sel_hi:[1,0]
	v_exp_f32_e32 v32, v32
	v_exp_f32_e32 v29, v29
	v_pk_mul_f32 v[16:17], v[20:21], v[16:17]
	v_pk_mul_f32 v[20:21], v[22:23], v[144:145] op_sel_hi:[1,0]
	v_mul_f32_e32 v30, 0xbfb8aa3b, v28
	v_pk_mul_f32 v[22:23], v[20:21], s[98:99] op_sel_hi:[1,0]
	s_nop 0
	v_exp_f32_e32 v22, v22
	v_exp_f32_e32 v23, v23
	v_add_f32_e32 v28, 1.0, v32
	v_add_f32_e32 v29, 1.0, v29
	v_exp_f32_e32 v30, v30
	v_exp_f32_e32 v31, v31
	v_rcp_f32_e32 v28, v28
	v_rcp_f32_e32 v29, v29
	v_pk_add_f32 v[22:23], v[22:23], 1.0 op_sel_hi:[1,0]
	s_nop 0
	v_rcp_f32_e32 v22, v22
	v_rcp_f32_e32 v23, v23
	v_add_f32_e32 v30, 1.0, v30
	v_add_f32_e32 v31, 1.0, v31
	v_pk_mul_f32 v[28:29], v[16:17], v[28:29]
	v_pk_mul_f32 v[16:17], v[18:19], v[144:145] op_sel_hi:[1,0]
	v_fmamk_f32 v142, v142, 0x3a800000, v226
	v_rcp_f32_e32 v30, v30
	v_rcp_f32_e32 v31, v31
	v_pk_mul_f32 v[16:17], v[20:21], v[16:17]
	v_rsq_f32_e32 v142, v142
	v_pk_mul_f32 v[20:21], v[16:17], v[22:23]
	v_add_u32_e32 v22, 0xa0, v126
	v_cvt_pk_bf16_f32 v19, v20, v21
	v_mad_i64_i32 v[20:21], s[22:23], v22, s65, v[114:115]
	v_lshl_add_u64 v[20:21], v[20:21], 0, s[68:69]
	v_pk_mul_f32 v[26:27], v[26:27], v[30:31]
	v_lshl_add_u64 v[20:21], v[20:21], 0, s[48:49]
	v_cvt_pk_bf16_f32 v16, v24, v25
	v_cvt_pk_bf16_f32 v17, v26, v27
	v_cvt_pk_bf16_f32 v18, v28, v29
	v_pk_mul_f32 v[12:13], v[12:13], v[142:143] op_sel_hi:[1,0]
	v_lshl_add_u64 v[20:21], v[20:21], 0, v[110:111]
	global_store_dwordx4 v[20:21], v[16:19], off
	v_pk_mul_f32 v[8:9], v[8:9], v[142:143] op_sel_hi:[1,0]
	s_nop 0
	v_pk_mul_f32 v[16:17], v[12:13], s[98:99] op_sel_hi:[1,0]
	s_nop 0
	v_exp_f32_e32 v16, v16
	v_exp_f32_e32 v17, v17
	v_pk_mul_f32 v[8:9], v[12:13], v[8:9]
	v_pk_add_f32 v[16:17], v[16:17], 1.0 op_sel_hi:[1,0]
	s_nop 0
	v_rcp_f32_e32 v16, v16
	v_rcp_f32_e32 v17, v17
	v_pk_mul_f32 v[12:13], v[14:15], v[142:143] op_sel_hi:[1,0]
	v_pk_mul_f32 v[4:5], v[4:5], v[142:143] op_sel_hi:[1,0]
	v_pk_mul_f32 v[10:11], v[10:11], v[142:143] op_sel_hi:[1,0]
	v_mul_f32_e32 v15, 0xbfb8aa3b, v13
	v_pk_mul_f32 v[8:9], v[8:9], v[16:17]
	v_mul_f32_e32 v16, 0xbfb8aa3b, v4
	v_pk_mul_f32 v[10:11], v[12:13], v[10:11]
	v_mul_f32_e32 v13, 0xbfb8aa3b, v5
	v_pk_mul_f32 v[0:1], v[0:1], v[142:143] op_sel_hi:[1,0]
	v_exp_f32_e32 v16, v16
	v_exp_f32_e32 v13, v13
	v_pk_mul_f32 v[0:1], v[4:5], v[0:1]
	v_pk_mul_f32 v[4:5], v[6:7], v[142:143] op_sel_hi:[1,0]
	v_mul_f32_e32 v14, 0xbfb8aa3b, v12
	v_pk_mul_f32 v[6:7], v[4:5], s[98:99] op_sel_hi:[1,0]
	s_nop 0
	v_exp_f32_e32 v6, v6
	v_exp_f32_e32 v7, v7
	v_add_f32_e32 v12, 1.0, v16
	v_add_f32_e32 v13, 1.0, v13
	v_exp_f32_e32 v14, v14
	v_exp_f32_e32 v15, v15
	v_rcp_f32_e32 v12, v12
	v_rcp_f32_e32 v13, v13
	v_pk_add_f32 v[6:7], v[6:7], 1.0 op_sel_hi:[1,0]
	s_nop 0
	v_rcp_f32_e32 v6, v6
	v_rcp_f32_e32 v7, v7
	v_add_f32_e32 v14, 1.0, v14
	v_add_f32_e32 v15, 1.0, v15
	v_pk_mul_f32 v[12:13], v[0:1], v[12:13]
	v_pk_mul_f32 v[0:1], v[2:3], v[142:143] op_sel_hi:[1,0]
	v_rcp_f32_e32 v14, v14
	v_rcp_f32_e32 v15, v15
	v_pk_mul_f32 v[0:1], v[4:5], v[0:1]
	v_cvt_pk_bf16_f32 v2, v12, v13
	v_pk_mul_f32 v[4:5], v[0:1], v[6:7]
	v_add_u32_e32 v6, 0xb0, v126
	v_cvt_pk_bf16_f32 v3, v4, v5
	v_mad_i64_i32 v[4:5], s[22:23], v6, s65, v[114:115]
	v_lshl_add_u64 v[4:5], v[4:5], 0, s[68:69]
	v_pk_mul_f32 v[10:11], v[10:11], v[14:15]
	v_lshl_add_u64 v[4:5], v[4:5], 0, s[48:49]
	v_cvt_pk_bf16_f32 v0, v8, v9
	v_cvt_pk_bf16_f32 v1, v10, v11
	v_lshl_add_u64 v[4:5], v[4:5], 0, v[110:111]
	s_mov_b64 s[6:7], -1
	global_store_dwordx4 v[4:5], v[0:3], off
	s_cbranch_vccnz .LBB0_1912
	s_andn2_b64 vcc, exec, s[30:31]
	s_cbranch_vccnz .LBB0_1911
	s_barrier
	s_branch .LBB0_1911
